# v23 + static wave-priority raise for the attn_small items of the mixer phase (they share each SIMD with an attn256 item)
# baseline (speedup 1.0000x reference)
; DEVI void run_phase(const Params& p, int ph, char* smem) {
;     ...
;       for (int it = blockIdx.x; it < tot; it += G) {
;         int i = it;
.LBB0_922:
	s_setprio 0
	v_readlane_b32 s4, v250, 1
	v_readlane_b32 s10, v250, 7
	v_readlane_b32 s0, v255, 17
	s_add_i32 s0, s0, s10
	v_readlane_b32 s5, v250, 2
	v_readlane_b32 s6, v250, 3
	v_readlane_b32 s7, v250, 4
	v_readlane_b32 s8, v250, 5
	v_readlane_b32 s9, v250, 6
	v_readlane_b32 s11, v250, 8
	s_cmpk_lg_u32 s10, 0x200
	s_cbranch_scc1 .Lms_std
	v_readlane_b32 s2, v250, 0
	s_cmpk_lt_u32 s2, 0x80
	s_cbranch_scc0 .Lms_std
	s_sub_i32 s2, s0, 0xe00
	s_cmpk_lt_u32 s2, 0x80
	s_cbranch_scc0 .Lms_a
	s_mov_b32 s0, s2
	s_branch .LBB0_923

; DEVI int tidx() { int t = threadIdx.x; asm volatile("" : "+v"(t)); return t; }
; DEVI float blo(unsigned u) { return __uint_as_float(u << 16); }
; DEVI float bhi(unsigned u) { return __uint_as_float(u & 0xffff0000u); }
; DEVI f32x4 ldnt4(const float* p_) { return __builtin_nontemporal_load((const f32x4*)p_); }
; template <int mode>
; DEVI void attn_small_item(const Params& p, int l, int sb, int hh, char* smem) {
;   float* qs = (float*)smem;
;   float* sc = qs + 512;
;   float* red = sc + 2048;
;   float* rinv = red + 2048;
;   const int tid = tidx(), lane = tid & 63, w = tid >> 6;
;   constexpr int nq = mode ? 8 : 4, nkeys = mode ? 132 : 256;
;   constexpr int NV = mode ? 34 : 32;
;   const int rowbase = T_P + sb * 4;
;   const u16* proj = (const u16*)(p.ws + WS_PROJ);
;   const u16* qx = (const u16*)(p.ws + WS_QX);
;   const int sub = lane >> 4, dl = lane & 15;
;   float4 kvs[16];
; #pragma unroll
;   for (int u = 0; u < 16; u++) {
;     const int key = w * 4 + u * 16 + sub;
;     float4 kv = make_float4(0.f, 0.f, 0.f, 0.f);
;     if (key < nkeys) {
;       if (mode) {
;         if (key < 128) { const f32x4 t4 = ldnt4(p.cache_swa_k + (((size_t)l * 128 + sb) * 128 + key) * 128 + hh * 64 + dl * 4); kv = make_float4(t4[0], t4[1], t4[2], t4[3]); }
;         else {
;           uint2 uu = *(const uint2*)(proj + (size_t)(rowbase + key - 128) * DIN + C_AK + hh * 64 + dl * 4);
;           kv = make_float4(blo(uu.x), bhi(uu.x), blo(uu.y), bhi(uu.y));
.LBB0_1090:
	s_andn2_b64 vcc, exec, s[2:3]
	s_cbranch_vccnz .LBB0_1711
	s_setprio 1
	v_readlane_b32 s2, v255, 17
	s_add_i32 s0, s2, 0xfffff900
	s_lshr_b32 s0, s0, 1
	s_and_b32 s14, s2, 1
	s_lshl_b32 s13, s0, 2
	s_lshl_b32 s0, s0, 7
	v_readlane_b32 s2, v255, 3
	v_readlane_b32 s4, v252, 54
	v_mov_b32_e32 v98, v145
	s_add_i32 s15, s13, 0x3f80
	s_lshl_b32 s12, s14, 6
	s_add_i32 s4, s2, s0
	s_lshl_b32 s2, s14, 8
	s_add_u32 s2, s20, s2
	v_ashrrev_i32_e32 v100, 6, v98
	v_and_b32_e32 v101, 15, v98
	v_bfe_u32 v0, v98, 4, 2
	v_lshlrev_b32_e32 v99, 2, v100
	v_readlane_b32 s5, v252, 55
	s_addc_u32 s3, s21, 0
	v_lshlrev_b32_e32 v10, 4, v101
	v_mov_b32_e32 v11, v1
	s_waitcnt vmcnt(0)
	v_or_b32_e32 v104, v99, v0
	v_writelane_b32 v252, s4, 54
	v_lshl_add_u64 v[12:13], s[2:3], 0, v[10:11]
	s_movk_i32 s2, 0x84
	v_lshlrev_b32_e32 v18, 2, v101
	v_writelane_b32 v252, s5, 55
	v_cmp_gt_i32_e64 s[66:67], s2, v104
	v_mov_b32_e32 v90, 0
	v_mov_b32_e32 v94, 0
	v_mov_b32_e32 v95, 0
	v_mov_b32_e32 v96, 0
	v_mov_b32_e32 v97, 0
	s_and_saveexec_b64 s[4:5], s[66:67]
	s_cbranch_execz .LBB0_1097
	s_movk_i32 s2, 0x7f
	v_cmp_lt_i32_e32 vcc, s2, v104
	s_and_saveexec_b64 s[2:3], vcc
	s_xor_b64 s[2:3], exec, s[2:3]
	s_cbranch_execz .LBB0_1094
	v_readlane_b32 s6, v250, 63
	v_readlane_b32 s7, v251, 0
	v_add_u32_e32 v0, s15, v104
	v_readlane_b32 s0, v252, 54
	v_mov_b64_e32 v[2:3], s[6:7]
	s_movk_i32 s6, 0x1400
	v_mad_u64_u32 v[2:3], s[6:7], v0, s6, v[2:3]
	v_readlane_b32 s1, v252, 55
	s_lshl_b32 s6, s12, 1
	s_mov_b32 s7, s1
	v_lshl_add_u64 v[2:3], v[2:3], 0, s[6:7]
	v_lshlrev_b32_e32 v0, 1, v18
	v_lshl_add_u64 v[2:3], v[2:3], 0, v[0:1]
	global_load_dwordx2 v[2:3], v[2:3], off offset:512
	s_waitcnt vmcnt(0)
	v_lshlrev_b32_e32 v94, 16, v2
	v_and_b32_e32 v95, 0xffff0000, v2
	v_lshlrev_b32_e32 v96, 16, v3
	v_and_b32_e32 v97, 0xffff0000, v3
